# v79 + FC-WAIT in the FFN-up K-loop: LDS-read wait moved from in front of the barrier to counted lgkmcnt waits at the first consuming MFMA
# baseline (speedup 1.0000x reference)
; #define PG8_STAGE(bufoff, gbase, voff) do { _Pragma("unroll") for (int _i = 0; _i < 2; ++_i) \
;         __builtin_amdgcn_global_load_lds((const unsigned*)((const char*)(gbase) + (voff)[_i]), (PG8_LAS unsigned*)(lds + (bufoff) + ldsw + _i * 8192), 16, 0, 0); } while (0)
; #define PG8_LDA(dst, b, h) do { _Pragma("unroll") for (int m = 0; m < 4; ++m) _Pragma("unroll") for (int k = 0; k < 2; ++k) dst[m][k] = *(const PG8_LAS bf16x8*)(lds + PG8_SA(b, h) + aoff + m * 2048 + k * 1024); } while (0)
; #define PG8_LDB(dst, b, h) do { _Pragma("unroll") for (int n = 0; n < 2; ++n) _Pragma("unroll") for (int k = 0; k < 2; ++k) dst[n][k] = *(const PG8_LAS bf16x8*)(lds + PG8_SB(b, h) + boff + n * 2048 + k * 1024); } while (0)
; #define PG8_MMA(ai, bj, At, Bt) do { __builtin_amdgcn_s_setprio(1); _Pragma("unroll") for (int m = 0; m < 4; ++m) _Pragma("unroll") for (int n = 0; n < 2; ++n) _Pragma("unroll") for (int k = 0; k < 2; ++k) \
;         acc[ai][bj][m][n] = __builtin_amdgcn_mfma_f32_16x16x32_bf16(Bt[n][k], At[m][k], acc[ai][bj][m][n], 0, 0, 0); __builtin_amdgcn_s_setprio(0); } while (0)
; #define PG8_WAIT_V(n) asm volatile("s_waitcnt vmcnt(" #n ")" ::: "memory")
; #define PG8_WAIT_L(n) asm volatile("s_waitcnt lgkmcnt(" #n ")" ::: "memory")
; #define PG8_BAR __builtin_amdgcn_s_barrier()
; #define PG8_SCHED __builtin_amdgcn_sched_barrier(0)
; template <class Epi, class Sched, bool ALIGN_EPI = false, bool SP2 = false>
; __device__ __forceinline__ void gemm_phase(PG8_LAS unsigned char* lds, const Gemm g, const Sched& S, const Epi& E) {
;     ...
;             PG8_LDB(B0, 0, 0); PG8_LDB(B1, 0, 1); PG8_SCHED; PG8_LDA(At, 0, 0); PG8_STAGE(PG8_SA(1, 1), a1 + hstep, voffA);
;             PG8_WAIT_V(8); PG8_WAIT_L(0); PG8_BAR; PG8_MMA(0, 0, At, B0); PG8_MMA(0, 1, At, B1); PG8_BAR; PG8_SCHED;
;             PG8_LDA(At, 0, 1); PG8_STAGE(PG8_SB(0, 0), b2, voffB); PG8_STAGE(PG8_SB(0, 1), b2 + hstep, voffB); PG8_STAGE(PG8_SA(0, 0), a2, voffA);
;             PG8_WAIT_V(8); PG8_WAIT_L(0); PG8_BAR; PG8_MMA(1, 0, At, B0); PG8_MMA(1, 1, At, B1); PG8_BAR; PG8_SCHED;
.LBB0_1356:
	s_add_u32 s20, s18, 0x4000
	s_addc_u32 s21, s19, 0
	s_cmp_eq_u32 s68, 12
	s_cselect_b32 s64, s40, s20
	s_cselect_b32 s65, s11, s21
	s_cselect_b32 s62, s61, s66
	s_cselect_b32 s63, s9, s67
	s_add_u32 s20, s64, 0x8000
	s_addc_u32 s21, s65, 0
	s_add_i32 s69, 0, 0x10000
	s_add_i32 s72, 0, 0x14000
	v_add_u32_e32 v140, s69, v162
	v_add_u32_e32 v160, s72, v162
	ds_read_b128 v[128:131], v140
	ds_read_b128 v[132:135], v140 offset:1024
	ds_read_b128 v[136:139], v140 offset:2048
	ds_read_b128 v[140:143], v140 offset:3072
	ds_read_b128 v[156:159], v160
	ds_read_b128 v[164:167], v160 offset:1024
	ds_read_b128 v[168:171], v160 offset:2048
	ds_read_b128 v[172:175], v160 offset:3072
	s_add_i32 m0, s37, 0xc000
	ds_read_b128 v[176:179], v163
	ds_read_b128 v[180:183], v163 offset:1024
	ds_read_b128 v[184:187], v163 offset:2048
	ds_read_b128 v[188:191], v163 offset:3072
	ds_read_b128 v[192:195], v163 offset:4096
	ds_read_b128 v[196:199], v163 offset:5120
	ds_read_b128 v[200:203], v163 offset:6144
	ds_read_b128 v[204:207], v163 offset:7168
	global_load_lds_dwordx4 v152, s[18:19]
	s_add_i32 m0, s37, 0xe000
	s_nop 0
	global_load_lds_dwordx4 v154, s[18:19]
	s_waitcnt vmcnt(8)
	s_barrier
	s_waitcnt lgkmcnt(7)
	v_mfma_f32_16x16x32_bf16 v[124:127], v[128:131], v[176:179], v[124:127]
	v_mfma_f32_16x16x32_bf16 v[120:123], v[136:139], v[176:179], v[120:123]
	s_waitcnt lgkmcnt(5)
	v_mfma_f32_16x16x32_bf16 v[108:111], v[128:131], v[184:187], v[108:111]
	v_mfma_f32_16x16x32_bf16 v[104:107], v[136:139], v[184:187], v[104:107]
	s_waitcnt lgkmcnt(3)
	v_mfma_f32_16x16x32_bf16 v[92:95], v[128:131], v[192:195], v[92:95]
	v_mfma_f32_16x16x32_bf16 v[88:91], v[136:139], v[192:195], v[88:91]
	s_waitcnt lgkmcnt(1)
	v_mfma_f32_16x16x32_bf16 v[76:79], v[128:131], v[200:203], v[76:79]
	v_mfma_f32_16x16x32_bf16 v[72:75], v[136:139], v[200:203], v[72:75]
	v_mfma_f32_16x16x32_bf16 v[124:127], v[132:135], v[180:183], v[124:127]
	v_mfma_f32_16x16x32_bf16 v[120:123], v[140:143], v[180:183], v[120:123]
	v_mfma_f32_16x16x32_bf16 v[108:111], v[132:135], v[188:191], v[108:111]
	v_mfma_f32_16x16x32_bf16 v[104:107], v[140:143], v[188:191], v[104:107]
	v_mfma_f32_16x16x32_bf16 v[92:95], v[132:135], v[196:199], v[92:95]
	v_mfma_f32_16x16x32_bf16 v[88:91], v[140:143], v[196:199], v[88:91]
	s_waitcnt lgkmcnt(0)
	v_mfma_f32_16x16x32_bf16 v[76:79], v[132:135], v[204:207], v[76:79]
	v_mfma_f32_16x16x32_bf16 v[72:75], v[140:143], v[204:207], v[72:75]
	v_mfma_f32_16x16x32_bf16 v[116:119], v[156:159], v[176:179], v[116:119]
	v_mfma_f32_16x16x32_bf16 v[112:115], v[168:171], v[176:179], v[112:115]
	v_mfma_f32_16x16x32_bf16 v[100:103], v[156:159], v[184:187], v[100:103]
	v_mfma_f32_16x16x32_bf16 v[96:99], v[168:171], v[184:187], v[96:99]
	v_mfma_f32_16x16x32_bf16 v[84:87], v[156:159], v[192:195], v[84:87]
	v_mfma_f32_16x16x32_bf16 v[80:83], v[168:171], v[192:195], v[80:83]
	v_mfma_f32_16x16x32_bf16 v[68:71], v[156:159], v[200:203], v[68:71]
	v_mfma_f32_16x16x32_bf16 v[64:67], v[168:171], v[200:203], v[64:67]
	v_mfma_f32_16x16x32_bf16 v[116:119], v[164:167], v[180:183], v[116:119]
	v_mfma_f32_16x16x32_bf16 v[112:115], v[172:175], v[180:183], v[112:115]
	v_mfma_f32_16x16x32_bf16 v[100:103], v[164:167], v[188:191], v[100:103]
	v_mfma_f32_16x16x32_bf16 v[96:99], v[172:175], v[188:191], v[96:99]
	v_mfma_f32_16x16x32_bf16 v[84:87], v[164:167], v[196:199], v[84:87]
	v_mfma_f32_16x16x32_bf16 v[80:83], v[172:175], v[196:199], v[80:83]
	v_mfma_f32_16x16x32_bf16 v[68:71], v[164:167], v[204:207], v[68:71]
	v_mfma_f32_16x16x32_bf16 v[64:67], v[172:175], v[204:207], v[64:67]
	s_barrier
	s_add_i32 s69, s69, s30
	s_mov_b32 m0, s69
	ds_read_b128 v[176:179], v163 offset:16384
	ds_read_b128 v[180:183], v163 offset:17408
	ds_read_b128 v[184:187], v163 offset:18432
	ds_read_b128 v[188:191], v163 offset:19456
	ds_read_b128 v[192:195], v163 offset:20480
	ds_read_b128 v[196:199], v163 offset:21504
	ds_read_b128 v[200:203], v163 offset:22528
	ds_read_b128 v[204:207], v163 offset:23552
	global_load_lds_dwordx4 v148, s[62:63]
	s_add_i32 m0, s69, 0x2000
	s_add_u32 s70, s62, 0x4000
	s_addc_u32 s71, s63, 0
	s_add_i32 s69, s72, s30
	global_load_lds_dwordx4 v144, s[62:63]
	s_mov_b32 m0, s69
	s_nop 0
	global_load_lds_dwordx4 v148, s[70:71]
	s_add_i32 m0, s69, 0x2000
	s_nop 0
	global_load_lds_dwordx4 v144, s[70:71]
	s_mov_b32 m0, s37
	s_nop 0
	global_load_lds_dwordx4 v150, s[64:65]
	s_mov_b32 m0, s39
	s_nop 0
	global_load_lds_dwordx4 v146, s[64:65]
	s_waitcnt vmcnt(8)
	s_barrier
	s_waitcnt lgkmcnt(7)
	v_mfma_f32_16x16x32_bf16 v[60:63], v[128:131], v[176:179], v[60:63]
	v_mfma_f32_16x16x32_bf16 v[56:59], v[136:139], v[176:179], v[56:59]
	s_waitcnt lgkmcnt(5)
	v_mfma_f32_16x16x32_bf16 v[44:47], v[128:131], v[184:187], v[44:47]
	v_mfma_f32_16x16x32_bf16 v[40:43], v[136:139], v[184:187], v[40:43]
	s_waitcnt lgkmcnt(3)
	v_mfma_f32_16x16x32_bf16 v[28:31], v[128:131], v[192:195], v[28:31]
	v_mfma_f32_16x16x32_bf16 v[24:27], v[136:139], v[192:195], v[24:27]
	s_waitcnt lgkmcnt(1)
	v_mfma_f32_16x16x32_bf16 v[12:15], v[128:131], v[200:203], v[12:15]
	v_mfma_f32_16x16x32_bf16 v[8:11], v[136:139], v[200:203], v[8:11]
	v_mfma_f32_16x16x32_bf16 v[60:63], v[132:135], v[180:183], v[60:63]
	v_mfma_f32_16x16x32_bf16 v[56:59], v[140:143], v[180:183], v[56:59]
	v_mfma_f32_16x16x32_bf16 v[44:47], v[132:135], v[188:191], v[44:47]
	v_mfma_f32_16x16x32_bf16 v[40:43], v[140:143], v[188:191], v[40:43]
	v_mfma_f32_16x16x32_bf16 v[28:31], v[132:135], v[196:199], v[28:31]
	v_mfma_f32_16x16x32_bf16 v[24:27], v[140:143], v[196:199], v[24:27]
	s_waitcnt lgkmcnt(0)
	v_mfma_f32_16x16x32_bf16 v[12:15], v[132:135], v[204:207], v[12:15]
	v_mfma_f32_16x16x32_bf16 v[8:11], v[140:143], v[204:207], v[8:11]
	v_mfma_f32_16x16x32_bf16 v[52:55], v[156:159], v[176:179], v[52:55]
	v_mfma_f32_16x16x32_bf16 v[48:51], v[168:171], v[176:179], v[48:51]
	v_mfma_f32_16x16x32_bf16 v[36:39], v[156:159], v[184:187], v[36:39]
	v_mfma_f32_16x16x32_bf16 v[32:35], v[168:171], v[184:187], v[32:35]
	v_mfma_f32_16x16x32_bf16 v[20:23], v[156:159], v[192:195], v[20:23]
	v_mfma_f32_16x16x32_bf16 v[16:19], v[168:171], v[192:195], v[16:19]
	v_mfma_f32_16x16x32_bf16 v[4:7], v[156:159], v[200:203], v[4:7]
	v_mfma_f32_16x16x32_bf16 v[0:3], v[168:171], v[200:203], v[0:3]
	v_mfma_f32_16x16x32_bf16 v[52:55], v[164:167], v[180:183], v[52:55]
	v_mfma_f32_16x16x32_bf16 v[48:51], v[172:175], v[180:183], v[48:51]
	v_mfma_f32_16x16x32_bf16 v[36:39], v[164:167], v[188:191], v[36:39]
	v_mfma_f32_16x16x32_bf16 v[32:35], v[172:175], v[188:191], v[32:35]
	v_mfma_f32_16x16x32_bf16 v[20:23], v[164:167], v[196:199], v[20:23]
	v_mfma_f32_16x16x32_bf16 v[16:19], v[172:175], v[196:199], v[16:19]
	v_mfma_f32_16x16x32_bf16 v[4:7], v[164:167], v[204:207], v[4:7]
	v_mfma_f32_16x16x32_bf16 v[0:3], v[172:175], v[204:207], v[0:3]
	s_barrier
; #define PG8_STAGE(bufoff, gbase, voff) do { _Pragma("unroll") for (int _i = 0; _i < 2; ++_i) \
;         __builtin_amdgcn_global_load_lds((const unsigned*)((const char*)(gbase) + (voff)[_i]), (PG8_LAS unsigned*)(lds + (bufoff) + ldsw + _i * 8192), 16, 0, 0); } while (0)
; #define PG8_LDA(dst, b, h) do { _Pragma("unroll") for (int m = 0; m < 4; ++m) _Pragma("unroll") for (int k = 0; k < 2; ++k) dst[m][k] = *(const PG8_LAS bf16x8*)(lds + PG8_SA(b, h) + aoff + m * 2048 + k * 1024); } while (0)
; #define PG8_LDB(dst, b, h) do { _Pragma("unroll") for (int n = 0; n < 2; ++n) _Pragma("unroll") for (int k = 0; k < 2; ++k) dst[n][k] = *(const PG8_LAS bf16x8*)(lds + PG8_SB(b, h) + boff + n * 2048 + k * 1024); } while (0)
; #define PG8_MMA(ai, bj, At, Bt) do { __builtin_amdgcn_s_setprio(1); _Pragma("unroll") for (int m = 0; m < 4; ++m) _Pragma("unroll") for (int n = 0; n < 2; ++n) _Pragma("unroll") for (int k = 0; k < 2; ++k) \
;         acc[ai][bj][m][n] = __builtin_amdgcn_mfma_f32_16x16x32_bf16(Bt[n][k], At[m][k], acc[ai][bj][m][n], 0, 0, 0); __builtin_amdgcn_s_setprio(0); } while (0)
; #define PG8_WAIT_V(n) asm volatile("s_waitcnt vmcnt(" #n ")" ::: "memory")
; #define PG8_WAIT_L(n) asm volatile("s_waitcnt lgkmcnt(" #n ")" ::: "memory")
; #define PG8_BAR __builtin_amdgcn_s_barrier()
; #define PG8_SCHED __builtin_amdgcn_sched_barrier(0)
; template <class Epi, class Sched, bool ALIGN_EPI = false, bool SP2 = false>
; __device__ __forceinline__ void gemm_phase(PG8_LAS unsigned char* lds, const Gemm g, const Sched& S, const Epi& E) {
;     ...
;             PG8_LDB(B0, 1, 0); PG8_LDB(B1, 1, 1); PG8_SCHED; PG8_LDA(At, 1, 0); PG8_STAGE(PG8_SA(0, 1), a2 + hstep, voffA);
;             PG8_WAIT_V(8); PG8_WAIT_L(0); PG8_BAR; PG8_MMA(0, 0, At, B0); PG8_MMA(0, 1, At, B1); PG8_BAR; PG8_SCHED;
;             PG8_LDA(At, 1, 1); PG8_STAGE(PG8_SB(1, 0), b3, voffB); PG8_STAGE(PG8_SB(1, 1), b3 + hstep, voffB); PG8_STAGE(PG8_SA(1, 0), a3, voffA);
;             PG8_WAIT_V(8); PG8_WAIT_L(0); PG8_BAR; PG8_MMA(1, 0, At, B0); PG8_MMA(1, 1, At, B1); PG8_BAR; PG8_SCHED;
;     ...
;         if constexpr (ALIGN_EPI) { if (wr == 0) PG8_BAR; }
	s_add_i32 s69, 0, 0x18000
	s_add_i32 s70, 0, 0x1c000
	v_add_u32_e32 v140, s69, v162
	v_add_u32_e32 v160, s70, v162
	ds_read_b128 v[128:131], v140
	ds_read_b128 v[132:135], v140 offset:1024
	ds_read_b128 v[136:139], v140 offset:2048
	ds_read_b128 v[140:143], v140 offset:3072
	ds_read_b128 v[156:159], v160
	ds_read_b128 v[164:167], v160 offset:1024
	ds_read_b128 v[168:171], v160 offset:2048
	ds_read_b128 v[172:175], v160 offset:3072
	s_add_u32 s64, s64, 0x4000
	s_addc_u32 s65, s65, 0
	s_mov_b32 m0, s41
	ds_read_b128 v[176:179], v163 offset:32768
	ds_read_b128 v[180:183], v163 offset:33792
	ds_read_b128 v[184:187], v163 offset:34816
	ds_read_b128 v[188:191], v163 offset:35840
	ds_read_b128 v[192:195], v163 offset:36864
	ds_read_b128 v[196:199], v163 offset:37888
	ds_read_b128 v[200:203], v163 offset:38912
	ds_read_b128 v[204:207], v163 offset:39936
	global_load_lds_dwordx4 v150, s[64:65]
	s_mov_b32 m0, s42
	s_nop 0
	global_load_lds_dwordx4 v146, s[64:65]
	s_waitcnt vmcnt(8)
	s_barrier
	s_waitcnt lgkmcnt(7)
	v_mfma_f32_16x16x32_bf16 v[124:127], v[128:131], v[176:179], v[124:127]
	v_mfma_f32_16x16x32_bf16 v[120:123], v[136:139], v[176:179], v[120:123]
	s_waitcnt lgkmcnt(5)
	v_mfma_f32_16x16x32_bf16 v[108:111], v[128:131], v[184:187], v[108:111]
	v_mfma_f32_16x16x32_bf16 v[104:107], v[136:139], v[184:187], v[104:107]
	s_waitcnt lgkmcnt(3)
	v_mfma_f32_16x16x32_bf16 v[92:95], v[128:131], v[192:195], v[92:95]
	v_mfma_f32_16x16x32_bf16 v[88:91], v[136:139], v[192:195], v[88:91]
	s_waitcnt lgkmcnt(1)
	v_mfma_f32_16x16x32_bf16 v[76:79], v[128:131], v[200:203], v[76:79]
	v_mfma_f32_16x16x32_bf16 v[72:75], v[136:139], v[200:203], v[72:75]
	v_mfma_f32_16x16x32_bf16 v[124:127], v[132:135], v[180:183], v[124:127]
	v_mfma_f32_16x16x32_bf16 v[120:123], v[140:143], v[180:183], v[120:123]
	v_mfma_f32_16x16x32_bf16 v[108:111], v[132:135], v[188:191], v[108:111]
	v_mfma_f32_16x16x32_bf16 v[104:107], v[140:143], v[188:191], v[104:107]
	v_mfma_f32_16x16x32_bf16 v[92:95], v[132:135], v[196:199], v[92:95]
	v_mfma_f32_16x16x32_bf16 v[88:91], v[140:143], v[196:199], v[88:91]
	s_waitcnt lgkmcnt(0)
	v_mfma_f32_16x16x32_bf16 v[76:79], v[132:135], v[204:207], v[76:79]
	v_mfma_f32_16x16x32_bf16 v[72:75], v[140:143], v[204:207], v[72:75]
	v_mfma_f32_16x16x32_bf16 v[116:119], v[156:159], v[176:179], v[116:119]
	v_mfma_f32_16x16x32_bf16 v[112:115], v[168:171], v[176:179], v[112:115]
	v_mfma_f32_16x16x32_bf16 v[100:103], v[156:159], v[184:187], v[100:103]
	v_mfma_f32_16x16x32_bf16 v[96:99], v[168:171], v[184:187], v[96:99]
	v_mfma_f32_16x16x32_bf16 v[84:87], v[156:159], v[192:195], v[84:87]
	v_mfma_f32_16x16x32_bf16 v[80:83], v[168:171], v[192:195], v[80:83]
	v_mfma_f32_16x16x32_bf16 v[68:71], v[156:159], v[200:203], v[68:71]
	v_mfma_f32_16x16x32_bf16 v[64:67], v[168:171], v[200:203], v[64:67]
	v_mfma_f32_16x16x32_bf16 v[116:119], v[164:167], v[180:183], v[116:119]
	v_mfma_f32_16x16x32_bf16 v[112:115], v[172:175], v[180:183], v[112:115]
	v_mfma_f32_16x16x32_bf16 v[100:103], v[164:167], v[188:191], v[100:103]
	v_mfma_f32_16x16x32_bf16 v[96:99], v[172:175], v[188:191], v[96:99]
	v_mfma_f32_16x16x32_bf16 v[84:87], v[164:167], v[196:199], v[84:87]
	v_mfma_f32_16x16x32_bf16 v[80:83], v[172:175], v[196:199], v[80:83]
	v_mfma_f32_16x16x32_bf16 v[68:71], v[164:167], v[204:207], v[68:71]
	v_mfma_f32_16x16x32_bf16 v[64:67], v[172:175], v[204:207], v[64:67]
	s_barrier
	s_add_u32 s64, s62, 0x8000
	s_addc_u32 s65, s63, 0
	s_add_i32 s69, s69, s30
	s_mov_b32 m0, s69
	ds_read_b128 v[176:179], v163 offset:49152
	ds_read_b128 v[180:183], v163 offset:50176
	ds_read_b128 v[184:187], v163 offset:51200
	ds_read_b128 v[188:191], v163 offset:52224
	ds_read_b128 v[192:195], v163 offset:53248
	ds_read_b128 v[196:199], v163 offset:54272
	ds_read_b128 v[200:203], v163 offset:55296
	ds_read_b128 v[204:207], v163 offset:56320
	global_load_lds_dwordx4 v148, s[64:65]
	s_add_i32 m0, s69, 0x2000
	s_add_u32 s62, s62, 0xc000
	v_lshl_add_u64 v[160:161], s[64:65], 0, v[144:145]
	s_addc_u32 s63, s63, 0
	s_add_i32 s64, s70, s30
	global_load_lds_dwordx4 v[160:161], off
	s_mov_b32 m0, s64
	s_nop 0
	global_load_lds_dwordx4 v148, s[62:63]
	s_add_i32 m0, s64, 0x2000
	s_nop 0
	global_load_lds_dwordx4 v144, s[62:63]
	s_mov_b32 m0, s54
	s_nop 0
	global_load_lds_dwordx4 v150, s[20:21]
	s_mov_b32 m0, s55
	s_nop 0
	global_load_lds_dwordx4 v146, s[20:21]
	s_waitcnt vmcnt(8)
	s_barrier
	s_waitcnt lgkmcnt(7)
	v_mfma_f32_16x16x32_bf16 v[60:63], v[128:131], v[176:179], v[60:63]
	v_mfma_f32_16x16x32_bf16 v[56:59], v[136:139], v[176:179], v[56:59]
	s_waitcnt lgkmcnt(5)
	v_mfma_f32_16x16x32_bf16 v[44:47], v[128:131], v[184:187], v[44:47]
	v_mfma_f32_16x16x32_bf16 v[40:43], v[136:139], v[184:187], v[40:43]
	s_waitcnt lgkmcnt(3)
	v_mfma_f32_16x16x32_bf16 v[28:31], v[128:131], v[192:195], v[28:31]
	v_mfma_f32_16x16x32_bf16 v[24:27], v[136:139], v[192:195], v[24:27]
	s_waitcnt lgkmcnt(1)
	v_mfma_f32_16x16x32_bf16 v[12:15], v[128:131], v[200:203], v[12:15]
	v_mfma_f32_16x16x32_bf16 v[8:11], v[136:139], v[200:203], v[8:11]
	v_mfma_f32_16x16x32_bf16 v[60:63], v[132:135], v[180:183], v[60:63]
	v_mfma_f32_16x16x32_bf16 v[56:59], v[140:143], v[180:183], v[56:59]
	v_mfma_f32_16x16x32_bf16 v[44:47], v[132:135], v[188:191], v[44:47]
	v_mfma_f32_16x16x32_bf16 v[40:43], v[140:143], v[188:191], v[40:43]
	v_mfma_f32_16x16x32_bf16 v[28:31], v[132:135], v[196:199], v[28:31]
	v_mfma_f32_16x16x32_bf16 v[24:27], v[140:143], v[196:199], v[24:27]
	s_waitcnt lgkmcnt(0)
	v_mfma_f32_16x16x32_bf16 v[12:15], v[132:135], v[204:207], v[12:15]
	v_mfma_f32_16x16x32_bf16 v[8:11], v[140:143], v[204:207], v[8:11]
	v_mfma_f32_16x16x32_bf16 v[52:55], v[156:159], v[176:179], v[52:55]
	v_mfma_f32_16x16x32_bf16 v[48:51], v[168:171], v[176:179], v[48:51]
	v_mfma_f32_16x16x32_bf16 v[36:39], v[156:159], v[184:187], v[36:39]
	v_mfma_f32_16x16x32_bf16 v[32:35], v[168:171], v[184:187], v[32:35]
	v_mfma_f32_16x16x32_bf16 v[20:23], v[156:159], v[192:195], v[20:23]
	v_mfma_f32_16x16x32_bf16 v[16:19], v[168:171], v[192:195], v[16:19]
	v_mfma_f32_16x16x32_bf16 v[4:7], v[156:159], v[200:203], v[4:7]
	v_mfma_f32_16x16x32_bf16 v[0:3], v[168:171], v[200:203], v[0:3]
	v_mfma_f32_16x16x32_bf16 v[52:55], v[164:167], v[180:183], v[52:55]
	v_mfma_f32_16x16x32_bf16 v[48:51], v[172:175], v[180:183], v[48:51]
	v_mfma_f32_16x16x32_bf16 v[36:39], v[164:167], v[188:191], v[36:39]
	v_mfma_f32_16x16x32_bf16 v[32:35], v[172:175], v[188:191], v[32:35]
	v_mfma_f32_16x16x32_bf16 v[20:23], v[164:167], v[196:199], v[20:23]
	v_mfma_f32_16x16x32_bf16 v[16:19], v[172:175], v[196:199], v[16:19]
	v_mfma_f32_16x16x32_bf16 v[4:7], v[164:167], v[204:207], v[4:7]
	v_mfma_f32_16x16x32_bf16 v[0:3], v[172:175], v[204:207], v[0:3]
	s_barrier
	s_add_i32 s68, s68, 2
	s_add_u32 s18, s18, 0x10000
	s_addc_u32 s19, s19, 0
	s_add_u32 s66, s66, 0x10000
	s_addc_u32 s67, s67, 0
	s_cmp_gt_u32 s68, 13
	s_cbranch_scc0 .LBB0_1356
	s_and_b64 vcc, exec, s[6:7]
	s_cbranch_vccz .LBB0_1359
	s_barrier
